# adaLN item: silu(c) LDS fill loop de-serialised (18 loads in flight, one wait) in both copies
# baseline (speedup 1.0000x reference)
.LBB0_513:
	global_load_dword v28, v6, s[6:7]
	v_add_u32_e32 v46, 0x800, v6
	global_load_dword v29, v46, s[6:7]
	v_add_u32_e32 v46, 0x1000, v6
	global_load_dword v30, v46, s[6:7]
	v_add_u32_e32 v46, 0x1800, v6
	global_load_dword v31, v46, s[6:7]
	v_add_u32_e32 v46, 0x2000, v6
	global_load_dword v32, v46, s[6:7]
	v_add_u32_e32 v46, 0x2800, v6
	global_load_dword v33, v46, s[6:7]
	v_add_u32_e32 v46, 0x3000, v6
	global_load_dword v34, v46, s[6:7]
	v_add_u32_e32 v46, 0x3800, v6
	global_load_dword v35, v46, s[6:7]
	v_add_u32_e32 v46, 0x4000, v6
	global_load_dword v36, v46, s[6:7]
	v_add_u32_e32 v46, 0x4800, v6
	global_load_dword v37, v46, s[6:7]
	v_add_u32_e32 v46, 0x5000, v6
	global_load_dword v38, v46, s[6:7]
	v_add_u32_e32 v46, 0x5800, v6
	global_load_dword v39, v46, s[6:7]
	v_add_u32_e32 v46, 0x6000, v6
	global_load_dword v40, v46, s[6:7]
	v_add_u32_e32 v46, 0x6800, v6
	global_load_dword v41, v46, s[6:7]
	v_add_u32_e32 v46, 0x7000, v6
	global_load_dword v42, v46, s[6:7]
	v_add_u32_e32 v46, 0x7800, v6
	global_load_dword v43, v46, s[6:7]
	global_load_dword v44, v6, s[10:11]
	v_add_u32_e32 v46, 0x800, v6
	global_load_dword v45, v46, s[10:11]
	s_waitcnt vmcnt(0)
	v_mul_f32_e32 v46, 0xbfb8aa3b, v28
	v_mul_f32_e32 v47, 0xbfb8aa3b, v29
	v_mul_f32_e32 v48, 0xbfb8aa3b, v30
	v_mul_f32_e32 v49, 0xbfb8aa3b, v31
	v_mul_f32_e32 v50, 0xbfb8aa3b, v32
	v_mul_f32_e32 v51, 0xbfb8aa3b, v33
	v_mul_f32_e32 v52, 0xbfb8aa3b, v34
	v_mul_f32_e32 v53, 0xbfb8aa3b, v35
	v_mul_f32_e32 v54, 0xbfb8aa3b, v36
	v_mul_f32_e32 v55, 0xbfb8aa3b, v37
	v_mul_f32_e32 v56, 0xbfb8aa3b, v38
	v_mul_f32_e32 v57, 0xbfb8aa3b, v39
	v_mul_f32_e32 v58, 0xbfb8aa3b, v40
	v_mul_f32_e32 v59, 0xbfb8aa3b, v41
	v_mul_f32_e32 v60, 0xbfb8aa3b, v42
	v_mul_f32_e32 v61, 0xbfb8aa3b, v43
	v_mul_f32_e32 v62, 0xbfb8aa3b, v44
	v_mul_f32_e32 v63, 0xbfb8aa3b, v45
	v_exp_f32_e32 v46, v46
	v_exp_f32_e32 v47, v47
	v_exp_f32_e32 v48, v48
	v_exp_f32_e32 v49, v49
	v_exp_f32_e32 v50, v50
	v_exp_f32_e32 v51, v51
	v_exp_f32_e32 v52, v52
	v_exp_f32_e32 v53, v53
	v_exp_f32_e32 v54, v54
	v_exp_f32_e32 v55, v55
	v_exp_f32_e32 v56, v56
	v_exp_f32_e32 v57, v57
	v_exp_f32_e32 v58, v58
	v_exp_f32_e32 v59, v59
	v_exp_f32_e32 v60, v60
	v_exp_f32_e32 v61, v61
	v_exp_f32_e32 v62, v62
	v_exp_f32_e32 v63, v63
	v_add_f32_e32 v46, 1.0, v46
	v_add_f32_e32 v47, 1.0, v47
	v_add_f32_e32 v48, 1.0, v48
	v_add_f32_e32 v49, 1.0, v49
	v_add_f32_e32 v50, 1.0, v50
	v_add_f32_e32 v51, 1.0, v51
	v_add_f32_e32 v52, 1.0, v52
	v_add_f32_e32 v53, 1.0, v53
	v_add_f32_e32 v54, 1.0, v54
	v_add_f32_e32 v55, 1.0, v55
	v_add_f32_e32 v56, 1.0, v56
	v_add_f32_e32 v57, 1.0, v57
	v_add_f32_e32 v58, 1.0, v58
	v_add_f32_e32 v59, 1.0, v59
	v_add_f32_e32 v60, 1.0, v60
	v_add_f32_e32 v61, 1.0, v61
	v_add_f32_e32 v62, 1.0, v62
	v_add_f32_e32 v63, 1.0, v63
	v_rcp_f32_e32 v46, v46
	v_rcp_f32_e32 v47, v47
	v_rcp_f32_e32 v48, v48
	v_rcp_f32_e32 v49, v49
	v_rcp_f32_e32 v50, v50
	v_rcp_f32_e32 v51, v51
	v_rcp_f32_e32 v52, v52
	v_rcp_f32_e32 v53, v53
	v_rcp_f32_e32 v54, v54
	v_rcp_f32_e32 v55, v55
	v_rcp_f32_e32 v56, v56
	v_rcp_f32_e32 v57, v57
	v_rcp_f32_e32 v58, v58
	v_rcp_f32_e32 v59, v59
	v_rcp_f32_e32 v60, v60
	v_rcp_f32_e32 v61, v61
	v_rcp_f32_e32 v62, v62
	v_rcp_f32_e32 v63, v63
	v_mul_f32_e32 v28, v28, v46
	v_mul_f32_e32 v29, v29, v47
	v_mul_f32_e32 v30, v30, v48
	v_mul_f32_e32 v31, v31, v49
	v_mul_f32_e32 v32, v32, v50
	v_mul_f32_e32 v33, v33, v51
	v_mul_f32_e32 v34, v34, v52
	v_mul_f32_e32 v35, v35, v53
	v_mul_f32_e32 v36, v36, v54
	v_mul_f32_e32 v37, v37, v55
	v_mul_f32_e32 v38, v38, v56
	v_mul_f32_e32 v39, v39, v57
	v_mul_f32_e32 v40, v40, v58
	v_mul_f32_e32 v41, v41, v59
	v_mul_f32_e32 v42, v42, v60
	v_mul_f32_e32 v43, v43, v61
	v_mul_f32_e32 v44, v44, v62
	v_mul_f32_e32 v45, v45, v63
	ds_write_b32 v6, v28
	ds_write_b32 v6, v29 offset:2048
	ds_write_b32 v6, v30 offset:4096
	ds_write_b32 v6, v31 offset:6144
	ds_write_b32 v6, v32 offset:8192
	ds_write_b32 v6, v33 offset:10240
	ds_write_b32 v6, v34 offset:12288
	ds_write_b32 v6, v35 offset:14336
	ds_write_b32 v6, v36 offset:16384
	ds_write_b32 v6, v37 offset:18432
	ds_write_b32 v6, v38 offset:20480
	ds_write_b32 v6, v39 offset:22528
	ds_write_b32 v6, v40 offset:24576
	ds_write_b32 v6, v41 offset:26624
	ds_write_b32 v6, v42 offset:28672
	ds_write_b32 v6, v43 offset:30720
	ds_write_b32 v6, v44 offset:32768
	ds_write_b32 v6, v45 offset:34816
	s_or_b64 exec, exec, s[22:23]
